# one L1 invalidate per layer (P2 cross-CU loads sc1); MG gate clamp folded into pk_fma; P1 K-loop hand-off barrier 4 MFMAs early with late priority raise
# baseline (speedup 1.0000x reference)
; #define PG8_STAGE(bufoff, gbase, voff) do { _Pragma("unroll") for (int _i = 0; _i < 2; ++_i) \
;         __builtin_amdgcn_global_load_lds((const GAS unsigned*)((const char*)(gbase) + (voff)[_i]), (LAS unsigned*)(lds + (bufoff) + ldsw + _i * 8192), 16, 0, 0); } while (0)
; #define PG8_LDA(dst, b, h) do { _Pragma("unroll") for (int m = 0; m < 4; ++m) _Pragma("unroll") for (int k = 0; k < 2; ++k) dst[m][k] = *(const LAS bf16x8*)(lds + PG8_SA(b, h) + aoff + m * 2048 + k * 1024); } while (0)
; #define PG8_LDB(dst, b, h) do { _Pragma("unroll") for (int n = 0; n < 2; ++n) _Pragma("unroll") for (int k = 0; k < 2; ++k) dst[n][k] = *(const LAS bf16x8*)(lds + PG8_SB(b, h) + boff + n * 2048 + k * 1024); } while (0)
; #define PG8_WAIT_V(n) asm volatile("s_waitcnt vmcnt(" #n ")" ::: "memory")
; #define PG8_WAIT_L(n) asm volatile("s_waitcnt lgkmcnt(" #n ")" ::: "memory")
; #define PG8_BAR __builtin_amdgcn_s_barrier()
; #define PG8_SCHED __builtin_amdgcn_sched_barrier(0)
; template <class Prog, bool ALIGN_EPI, bool NHALF = false, bool PITCHED = false, bool SLACK = false>
; __device__ __forceinline__ void gemm_phase(LAS unsigned char* lds, const int pitch, Prog& P, const int wave_, unsigned long long& t_k, unsigned long long& t_e) {
;     ...
;             PG8_LDB(B0, 0, 0); PG8_LDB(B1, 0, 1); PG8_SCHED; PG8_LDA(At, 0, 0); if (!(SLACK && SLACK_PRE && fst)) PG8_STAGE(PG8_SA(1, 1), a1 + hstep, voffA);
;             PG8_WAIT_F; PG8_WAIT_L(0); PG8_BAR; PG8_MMA(0, 0, At, B0); PG8_MMA(0, 1, At, B1); PG8_BAR; PG8_SCHED;
;             PG8_LDA(At, 0, 1); PG8_STAGE(PG8_SB(0, 0), b2, voffB2); PG8_STAGE(PG8_SB(0, 1), b2 + hstep2, voffB2); PG8_STAGE(PG8_SA(0, 0), a2, voffA2);
;             PG8_WAIT_F; PG8_WAIT_L(0); PG8_BAR; PG8_MMA(1, 0, At, B0); PG8_MMA(1, 1, At, B1); PG8_BAR; PG8_SCHED;
;             PG8_LDB(B0, 1, 0); PG8_LDB(B1, 1, 1); PG8_SCHED; PG8_LDA(At, 1, 0); PG8_STAGE(PG8_SA(0, 1), a2 + hstep2, voffA2);
;             if (SLACK_PRE) PG8_WAIT_F; else PG8_WAIT_V(8); PG8_WAIT_L(0); PG8_BAR; PG8_MMA(0, 0, At, B0); PG8_MMA(0, 1, At, B1); PG8_BAR; PG8_SCHED;
;             PG8_LDA(At, 1, 1); PG8_STAGE(PG8_SB(1, 0), b3, voffB2); PG8_STAGE(PG8_SB(1, 1), b3 + hstep2, voffB2); PG8_STAGE(PG8_SA(1, 0), a3, voffA2);
;             PG8_WAIT_V(8); PG8_WAIT_L(0); PG8_BAR; PG8_MMA(1, 0, At, B0); PG8_MMA(1, 1, At, B1); PG8_BAR; PG8_SCHED;
.Lwf0:
	s_waitcnt lgkmcnt(0)
	s_barrier
	s_waitcnt lgkmcnt(0)
	v_mfma_f32_16x16x32_bf16 v[88:91], v[0:3], v[56:59], 0
	v_mfma_f32_16x16x32_bf16 v[64:67], v[0:3], v[32:35], 0
	v_mfma_f32_16x16x32_bf16 v[68:71], v[8:11], v[32:35], 0
	v_mfma_f32_16x16x32_bf16 v[72:75], v[0:3], v[40:43], 0
	s_setprio 1
	v_mfma_f32_16x16x32_bf16 v[76:79], v[8:11], v[40:43], 0
	v_mfma_f32_16x16x32_bf16 v[80:83], v[0:3], v[48:51], 0
	v_mfma_f32_16x16x32_bf16 v[84:87], v[8:11], v[48:51], 0
	v_mfma_f32_16x16x32_bf16 v[96:99], v[4:7], v[60:63], v[88:91]
	v_mfma_f32_16x16x32_bf16 v[88:91], v[8:11], v[56:59], 0
	v_mfma_f32_16x16x32_bf16 v[64:67], v[4:7], v[36:39], v[64:67]
	v_mfma_f32_16x16x32_bf16 v[68:71], v[12:15], v[36:39], v[68:71]
	v_mfma_f32_16x16x32_bf16 v[72:75], v[4:7], v[44:47], v[72:75]
	v_mfma_f32_16x16x32_bf16 v[76:79], v[12:15], v[44:47], v[76:79]
	v_mfma_f32_16x16x32_bf16 v[80:83], v[4:7], v[52:55], v[80:83]
	v_mfma_f32_16x16x32_bf16 v[84:87], v[12:15], v[52:55], v[84:87]
	v_mfma_f32_16x16x32_bf16 v[100:103], v[12:15], v[60:63], v[88:91]
	s_setprio 0
	s_setprio 1
	v_mfma_f32_16x16x32_bf16 v[88:91], v[16:19], v[32:35], 0
	v_mfma_f32_16x16x32_bf16 v[32:35], v[24:27], v[32:35], 0
	v_mfma_f32_16x16x32_bf16 v[112:115], v[20:23], v[36:39], v[88:91]
	v_mfma_f32_16x16x32_bf16 v[32:35], v[28:31], v[36:39], v[32:35]
	v_mfma_f32_16x16x32_bf16 v[36:39], v[16:19], v[40:43], 0
	v_mfma_f32_16x16x32_bf16 v[40:43], v[24:27], v[40:43], 0
	v_mfma_f32_16x16x32_bf16 v[36:39], v[20:23], v[44:47], v[36:39]
	v_mfma_f32_16x16x32_bf16 v[40:43], v[28:31], v[44:47], v[40:43]
	v_mfma_f32_16x16x32_bf16 v[44:47], v[16:19], v[48:51], 0
	v_mfma_f32_16x16x32_bf16 v[48:51], v[24:27], v[48:51], 0
	v_mfma_f32_16x16x32_bf16 v[44:47], v[20:23], v[52:55], v[44:47]
	v_mfma_f32_16x16x32_bf16 v[48:51], v[28:31], v[52:55], v[48:51]
	s_barrier
	v_mfma_f32_16x16x32_bf16 v[52:55], v[16:19], v[56:59], 0
	v_mfma_f32_16x16x32_bf16 v[56:59], v[24:27], v[56:59], 0
	v_mfma_f32_16x16x32_bf16 v[52:55], v[20:23], v[60:63], v[52:55]
	v_mfma_f32_16x16x32_bf16 v[56:59], v[28:31], v[60:63], v[56:59]
	s_setprio 0
	s_add_i32 s8, s10, s59
	v_lshl_add_u64 v[190:191], s[48:49], 0, v[192:193]
	s_add_i32 s9, s8, 0x2000
	v_lshl_add_u64 v[130:131], v[190:191], 0, s[14:15]
	s_mov_b32 m0, s8
	v_lshl_add_u64 v[194:195], s[48:49], 0, v[156:157]
	s_add_u32 s18, s48, 0x40100
	ds_read_b128 v[60:63], v252 offset:16384
	ds_read_b128 v[88:91], v252 offset:17408
	ds_read_b128 v[92:95], v252 offset:18432
	ds_read_b128 v[104:107], v252 offset:19456
	ds_read_b128 v[108:111], v252 offset:20480
	ds_read_b128 v[116:119], v252 offset:21504
	ds_read_b128 v[120:123], v252 offset:22528
	ds_read_b128 v[124:127], v252 offset:23552
	global_load_lds_dwordx4 v[130:131], off
	v_lshl_add_u64 v[130:131], v[194:195], 0, s[14:15]
	s_mov_b32 m0, s9
	s_addc_u32 s19, s49, 0
	s_add_i32 s10, s11, s59
	global_load_lds_dwordx4 v[130:131], off
	v_lshl_add_u64 v[130:131], s[18:19], 0, v[192:193]
	s_mov_b32 m0, s10
	s_add_i32 s11, s10, 0x2000
	global_load_lds_dwordx4 v[130:131], off
	v_lshl_add_u64 v[130:131], s[18:19], 0, v[156:157]
	s_mov_b32 m0, s11
	v_lshl_add_u64 v[244:245], s[38:39], 0, v[152:153]
	global_load_lds_dwordx4 v[130:131], off
	v_lshl_add_u64 v[130:131], v[244:245], 0, s[14:15]
	s_mov_b32 m0, s60
	v_lshl_add_u64 v[246:247], s[38:39], 0, v[154:155]
	global_load_lds_dwordx4 v[130:131], off
	v_lshl_add_u64 v[130:131], v[246:247], 0, s[14:15]
	s_mov_b32 m0, s61
	s_nop 0
	global_load_lds_dwordx4 v[130:131], off
	s_waitcnt vmcnt(24)
	s_cmp_gt_u32 s16, 1
	s_cbranch_scc1 .Lwf1
	s_waitcnt vmcnt(16)
	s_cmp_gt_u32 s16, 0
	s_cbranch_scc1 .Lwf1
	s_waitcnt vmcnt(8)
.Lwf1:
	s_waitcnt lgkmcnt(0)
	s_barrier
	s_waitcnt lgkmcnt(0)
	v_mfma_f32_16x16x32_bf16 v[130:133], v[0:3], v[60:63], 0
	v_mfma_f32_16x16x32_bf16 v[140:143], v[0:3], v[92:95], 0
	v_mfma_f32_16x16x32_bf16 v[148:151], v[0:3], v[108:111], 0
	v_mfma_f32_16x16x32_bf16 v[0:3], v[0:3], v[120:123], 0
	s_setprio 1
	v_mfma_f32_16x16x32_bf16 v[132:135], v[4:7], v[88:91], v[130:133]
	v_mfma_f32_16x16x32_bf16 v[140:143], v[4:7], v[104:107], v[140:143]
	v_mfma_f32_16x16x32_bf16 v[148:151], v[4:7], v[116:119], v[148:151]
	v_mfma_f32_16x16x32_bf16 v[0:3], v[4:7], v[124:127], v[0:3]
	v_mfma_f32_16x16x32_bf16 v[4:7], v[8:11], v[120:123], 0
	v_mfma_f32_16x16x32_bf16 v[136:139], v[8:11], v[60:63], 0
	v_mfma_f32_16x16x32_bf16 v[144:147], v[8:11], v[92:95], 0
	v_mfma_f32_16x16x32_bf16 v[162:165], v[8:11], v[108:111], 0
	v_mfma_f32_16x16x32_bf16 v[4:7], v[12:15], v[124:127], v[4:7]
	v_mfma_f32_16x16x32_bf16 v[136:139], v[12:15], v[88:91], v[136:139]
	v_mfma_f32_16x16x32_bf16 v[144:147], v[12:15], v[104:107], v[144:147]
	v_mfma_f32_16x16x32_bf16 v[162:165], v[12:15], v[116:119], v[162:165]
	s_setprio 0
	s_setprio 1
	v_mfma_f32_16x16x32_bf16 v[8:11], v[16:19], v[60:63], 0
	v_mfma_f32_16x16x32_bf16 v[166:169], v[20:23], v[88:91], v[8:11]
	v_mfma_f32_16x16x32_bf16 v[8:11], v[24:27], v[60:63], 0
	v_mfma_f32_16x16x32_bf16 v[170:173], v[28:31], v[88:91], v[8:11]
	v_mfma_f32_16x16x32_bf16 v[8:11], v[16:19], v[92:95], 0
	v_mfma_f32_16x16x32_bf16 v[174:177], v[20:23], v[104:107], v[8:11]
	v_mfma_f32_16x16x32_bf16 v[8:11], v[24:27], v[92:95], 0
	v_mfma_f32_16x16x32_bf16 v[178:181], v[28:31], v[104:107], v[8:11]
	v_mfma_f32_16x16x32_bf16 v[8:11], v[16:19], v[108:111], 0
	v_mfma_f32_16x16x32_bf16 v[182:185], v[20:23], v[116:119], v[8:11]
	v_mfma_f32_16x16x32_bf16 v[8:11], v[24:27], v[108:111], 0
	v_mfma_f32_16x16x32_bf16 v[186:189], v[28:31], v[116:119], v[8:11]
	s_barrier
; #define PG8_STAGE(bufoff, gbase, voff) do { _Pragma("unroll") for (int _i = 0; _i < 2; ++_i) \
;         __builtin_amdgcn_global_load_lds((const GAS unsigned*)((const char*)(gbase) + (voff)[_i]), (LAS unsigned*)(lds + (bufoff) + ldsw + _i * 8192), 16, 0, 0); } while (0)
; #define PG8_LDA(dst, b, h) do { _Pragma("unroll") for (int m = 0; m < 4; ++m) _Pragma("unroll") for (int k = 0; k < 2; ++k) dst[m][k] = *(const LAS bf16x8*)(lds + PG8_SA(b, h) + aoff + m * 2048 + k * 1024); } while (0)
; #define PG8_LDB(dst, b, h) do { _Pragma("unroll") for (int n = 0; n < 2; ++n) _Pragma("unroll") for (int k = 0; k < 2; ++k) dst[n][k] = *(const LAS bf16x8*)(lds + PG8_SB(b, h) + boff + n * 2048 + k * 1024); } while (0)
; #define PG8_WAIT_V(n) asm volatile("s_waitcnt vmcnt(" #n ")" ::: "memory")
; #define PG8_WAIT_L(n) asm volatile("s_waitcnt lgkmcnt(" #n ")" ::: "memory")
; #define PG8_BAR __builtin_amdgcn_s_barrier()
; #define PG8_SCHED __builtin_amdgcn_sched_barrier(0)
; template <class Prog, bool ALIGN_EPI, bool NHALF = false, bool PITCHED = false, bool SLACK = false>
; __device__ __forceinline__ void gemm_phase(LAS unsigned char* lds, const int pitch, Prog& P, const int wave_, unsigned long long& t_k, unsigned long long& t_e) {
;     ...
;             PG8_LDB(B0, 0, 0); PG8_LDB(B1, 0, 1); PG8_SCHED; PG8_LDA(At, 0, 0); if (!(SLACK && SLACK_PRE && fst)) PG8_STAGE(PG8_SA(1, 1), a1 + hstep, voffA);
;             PG8_WAIT_F; PG8_WAIT_L(0); PG8_BAR; PG8_MMA(0, 0, At, B0); PG8_MMA(0, 1, At, B1); PG8_BAR; PG8_SCHED;
;             PG8_LDA(At, 0, 1); PG8_STAGE(PG8_SB(0, 0), b2, voffB2); PG8_STAGE(PG8_SB(0, 1), b2 + hstep2, voffB2); PG8_STAGE(PG8_SA(0, 0), a2, voffA2);
;             PG8_WAIT_F; PG8_WAIT_L(0); PG8_BAR; PG8_MMA(1, 0, At, B0); PG8_MMA(1, 1, At, B1); PG8_BAR; PG8_SCHED;
;             PG8_LDB(B0, 1, 0); PG8_LDB(B1, 1, 1); PG8_SCHED; PG8_LDA(At, 1, 0); PG8_STAGE(PG8_SA(0, 1), a2 + hstep2, voffA2);
;             if (SLACK_PRE) PG8_WAIT_F; else PG8_WAIT_V(8); PG8_WAIT_L(0); PG8_BAR; PG8_MMA(0, 0, At, B0); PG8_MMA(0, 1, At, B1); PG8_BAR; PG8_SCHED;
;             PG8_LDA(At, 1, 1); PG8_STAGE(PG8_SB(1, 0), b3, voffB2); PG8_STAGE(PG8_SB(1, 1), b3 + hstep2, voffB2); PG8_STAGE(PG8_SA(1, 0), a3, voffA2);
;             PG8_WAIT_V(8); PG8_WAIT_L(0); PG8_BAR; PG8_MMA(1, 0, At, B0); PG8_MMA(1, 1, At, B1); PG8_BAR; PG8_SCHED;
	v_mfma_f32_16x16x32_bf16 v[8:11], v[16:19], v[120:123], 0
	v_mfma_f32_16x16x32_bf16 v[196:199], v[20:23], v[124:127], v[8:11]
	v_mfma_f32_16x16x32_bf16 v[8:11], v[24:27], v[120:123], 0
	v_mfma_f32_16x16x32_bf16 v[200:203], v[28:31], v[124:127], v[8:11]
	s_setprio 0
	s_add_i32 s18, 0, 0x18000
	s_add_i32 s19, 0, 0x1c000
	v_add_u32_e32 v130, s18, v251
	v_add_u32_e32 v131, s19, v251
	s_nop 0
	ds_read_b128 v[8:11], v130
	ds_read_b128 v[12:15], v130 offset:1024
	ds_read_b128 v[16:19], v130 offset:2048
	ds_read_b128 v[20:23], v130 offset:3072
	ds_read_b128 v[204:207], v131
	ds_read_b128 v[208:211], v131 offset:1024
	ds_read_b128 v[212:215], v131 offset:2048
	ds_read_b128 v[216:219], v131 offset:3072
	s_add_u32 s16, s38, 0x40100
	s_addc_u32 s17, s39, 0
	s_mov_b32 m0, s62
	v_lshl_add_u64 v[88:89], s[16:17], 0, v[152:153]
	ds_read_b128 v[24:27], v252 offset:32768
	ds_read_b128 v[28:31], v252 offset:33792
	ds_read_b128 v[60:63], v252 offset:34816
	ds_read_b128 v[220:223], v252 offset:35840
	ds_read_b128 v[224:227], v252 offset:36864
	ds_read_b128 v[228:231], v252 offset:37888
	ds_read_b128 v[232:235], v252 offset:38912
	ds_read_b128 v[236:239], v252 offset:39936
	global_load_lds_dwordx4 v[88:89], off
	v_lshl_add_u64 v[88:89], s[16:17], 0, v[154:155]
	s_mov_b32 m0, s63
	s_nop 0
	global_load_lds_dwordx4 v[88:89], off
	s_waitcnt vmcnt(8)
	s_waitcnt lgkmcnt(0)
	s_barrier
	s_waitcnt lgkmcnt(0)
	v_mfma_f32_16x16x32_bf16 v[64:67], v[8:11], v[24:27], v[64:67]
	v_mfma_f32_16x16x32_bf16 v[124:127], v[12:15], v[28:31], v[64:67]
	v_mfma_f32_16x16x32_bf16 v[64:67], v[16:19], v[24:27], v[68:71]
	v_mfma_f32_16x16x32_bf16 v[120:123], v[20:23], v[28:31], v[64:67]
	s_setprio 1
	v_mfma_f32_16x16x32_bf16 v[64:67], v[8:11], v[60:63], v[72:75]
	v_mfma_f32_16x16x32_bf16 v[108:111], v[12:15], v[220:223], v[64:67]
	v_mfma_f32_16x16x32_bf16 v[64:67], v[16:19], v[60:63], v[76:79]
	v_mfma_f32_16x16x32_bf16 v[104:107], v[20:23], v[220:223], v[64:67]
	v_mfma_f32_16x16x32_bf16 v[64:67], v[8:11], v[224:227], v[80:83]
	v_mfma_f32_16x16x32_bf16 v[92:95], v[12:15], v[228:231], v[64:67]
	v_mfma_f32_16x16x32_bf16 v[64:67], v[16:19], v[224:227], v[84:87]
	v_mfma_f32_16x16x32_bf16 v[88:91], v[20:23], v[228:231], v[64:67]
	v_mfma_f32_16x16x32_bf16 v[64:67], v[8:11], v[232:235], v[96:99]
	v_mfma_f32_16x16x32_bf16 v[76:79], v[12:15], v[236:239], v[64:67]
	v_mfma_f32_16x16x32_bf16 v[64:67], v[16:19], v[232:235], v[100:103]
	v_mfma_f32_16x16x32_bf16 v[72:75], v[20:23], v[236:239], v[64:67]
	s_setprio 0
	s_setprio 1
	v_mfma_f32_16x16x32_bf16 v[64:67], v[204:207], v[24:27], v[112:115]
	v_mfma_f32_16x16x32_bf16 v[24:27], v[212:215], v[24:27], v[32:35]
	v_mfma_f32_16x16x32_bf16 v[112:115], v[216:219], v[28:31], v[24:27]
	v_mfma_f32_16x16x32_bf16 v[24:27], v[204:207], v[60:63], v[36:39]
	v_mfma_f32_16x16x32_bf16 v[100:103], v[208:211], v[220:223], v[24:27]
	v_mfma_f32_16x16x32_bf16 v[24:27], v[212:215], v[60:63], v[40:43]
	v_mfma_f32_16x16x32_bf16 v[96:99], v[216:219], v[220:223], v[24:27]
	v_mfma_f32_16x16x32_bf16 v[24:27], v[204:207], v[224:227], v[44:47]
	v_mfma_f32_16x16x32_bf16 v[84:87], v[208:211], v[228:231], v[24:27]
	v_mfma_f32_16x16x32_bf16 v[24:27], v[212:215], v[224:227], v[48:51]
	v_mfma_f32_16x16x32_bf16 v[80:83], v[216:219], v[228:231], v[24:27]
	v_mfma_f32_16x16x32_bf16 v[24:27], v[204:207], v[232:235], v[52:55]
	s_barrier
; #define PG8_STAGE(bufoff, gbase, voff) do { _Pragma("unroll") for (int _i = 0; _i < 2; ++_i) \
;         __builtin_amdgcn_global_load_lds((const GAS unsigned*)((const char*)(gbase) + (voff)[_i]), (LAS unsigned*)(lds + (bufoff) + ldsw + _i * 8192), 16, 0, 0); } while (0)
; #define PG8_LDA(dst, b, h) do { _Pragma("unroll") for (int m = 0; m < 4; ++m) _Pragma("unroll") for (int k = 0; k < 2; ++k) dst[m][k] = *(const LAS bf16x8*)(lds + PG8_SA(b, h) + aoff + m * 2048 + k * 1024); } while (0)
; #define PG8_LDB(dst, b, h) do { _Pragma("unroll") for (int n = 0; n < 2; ++n) _Pragma("unroll") for (int k = 0; k < 2; ++k) dst[n][k] = *(const LAS bf16x8*)(lds + PG8_SB(b, h) + boff + n * 2048 + k * 1024); } while (0)
; #define PG8_WAIT_V(n) asm volatile("s_waitcnt vmcnt(" #n ")" ::: "memory")
; #define PG8_WAIT_L(n) asm volatile("s_waitcnt lgkmcnt(" #n ")" ::: "memory")
; #define PG8_BAR __builtin_amdgcn_s_barrier()
; #define PG8_SCHED __builtin_amdgcn_sched_barrier(0)
; template <class Prog, bool ALIGN_EPI, bool NHALF = false, bool PITCHED = false, bool SLACK = false>
; __device__ __forceinline__ void gemm_phase(LAS unsigned char* lds, const int pitch, Prog& P, const int wave_, unsigned long long& t_k, unsigned long long& t_e) {
;     ...
;             PG8_LDB(B0, 0, 0); PG8_LDB(B1, 0, 1); PG8_SCHED; PG8_LDA(At, 0, 0); if (!(SLACK && SLACK_PRE && fst)) PG8_STAGE(PG8_SA(1, 1), a1 + hstep, voffA);
;             PG8_WAIT_F; PG8_WAIT_L(0); PG8_BAR; PG8_MMA(0, 0, At, B0); PG8_MMA(0, 1, At, B1); PG8_BAR; PG8_SCHED;
;             PG8_LDA(At, 0, 1); PG8_STAGE(PG8_SB(0, 0), b2, voffB2); PG8_STAGE(PG8_SB(0, 1), b2 + hstep2, voffB2); PG8_STAGE(PG8_SA(0, 0), a2, voffA2);
;             PG8_WAIT_F; PG8_WAIT_L(0); PG8_BAR; PG8_MMA(1, 0, At, B0); PG8_MMA(1, 1, At, B1); PG8_BAR; PG8_SCHED;
;             PG8_LDB(B0, 1, 0); PG8_LDB(B1, 1, 1); PG8_SCHED; PG8_LDA(At, 1, 0); PG8_STAGE(PG8_SA(0, 1), a2 + hstep2, voffA2);
;             if (SLACK_PRE) PG8_WAIT_F; else PG8_WAIT_V(8); PG8_WAIT_L(0); PG8_BAR; PG8_MMA(0, 0, At, B0); PG8_MMA(0, 1, At, B1); PG8_BAR; PG8_SCHED;
;             PG8_LDA(At, 1, 1); PG8_STAGE(PG8_SB(1, 0), b3, voffB2); PG8_STAGE(PG8_SB(1, 1), b3 + hstep2, voffB2); PG8_STAGE(PG8_SA(1, 0), a3, voffA2);
;             PG8_WAIT_V(8); PG8_WAIT_L(0); PG8_BAR; PG8_MMA(1, 0, At, B0); PG8_MMA(1, 1, At, B1); PG8_BAR; PG8_SCHED;
	v_mfma_f32_16x16x32_bf16 v[68:71], v[208:211], v[236:239], v[24:27]
	v_mfma_f32_16x16x32_bf16 v[24:27], v[212:215], v[232:235], v[56:59]
	v_mfma_f32_16x16x32_bf16 v[116:119], v[208:211], v[28:31], v[64:67]
	v_mfma_f32_16x16x32_bf16 v[64:67], v[216:219], v[236:239], v[24:27]
	s_setprio 0
	s_add_i32 s16, s18, s59
	s_mov_b64 s[34:35], 0x180
	s_add_i32 s17, s16, 0x2000
	s_nop 0
	v_lshl_add_u64 v[24:25], v[190:191], 0, s[34:35]
	s_mov_b32 m0, s16
	s_add_u32 s24, s48, 0x40180
	ds_read_b128 v[32:35], v252 offset:49152
	ds_read_b128 v[36:39], v252 offset:50176
	ds_read_b128 v[220:223], v252 offset:51200
	ds_read_b128 v[224:227], v252 offset:52224
	ds_read_b128 v[228:231], v252 offset:53248
	ds_read_b128 v[232:235], v252 offset:54272
	ds_read_b128 v[236:239], v252 offset:55296
	ds_read_b128 v[240:243], v252 offset:56320
	global_load_lds_dwordx4 v[24:25], off
	v_lshl_add_u64 v[24:25], v[194:195], 0, s[34:35]
	s_mov_b32 m0, s17
	s_addc_u32 s25, s49, 0
	s_add_i32 s18, s19, s59
	global_load_lds_dwordx4 v[24:25], off
	v_lshl_add_u64 v[24:25], s[24:25], 0, v[192:193]
	s_mov_b32 m0, s18
	s_add_i32 s19, s18, 0x2000
	global_load_lds_dwordx4 v[24:25], off
	v_lshl_add_u64 v[24:25], s[24:25], 0, v[156:157]
	s_mov_b32 m0, s19
	s_nop 0
	global_load_lds_dwordx4 v[24:25], off
	v_lshl_add_u64 v[24:25], v[244:245], 0, s[34:35]
	s_mov_b32 m0, s81
	s_nop 0
	global_load_lds_dwordx4 v[24:25], off
	v_lshl_add_u64 v[24:25], v[246:247], 0, s[34:35]
	s_mov_b32 m0, s82
	s_nop 0
	global_load_lds_dwordx4 v[24:25], off
	s_waitcnt vmcnt(8)
	s_waitcnt lgkmcnt(0)
	s_barrier
	s_waitcnt lgkmcnt(0)
	v_mfma_f32_16x16x32_bf16 v[24:27], v[8:11], v[32:35], v[132:135]
	v_mfma_f32_16x16x32_bf16 v[60:63], v[12:15], v[36:39], v[24:27]
	v_mfma_f32_16x16x32_bf16 v[24:27], v[16:19], v[32:35], v[136:139]
	v_mfma_f32_16x16x32_bf16 v[56:59], v[20:23], v[36:39], v[24:27]
	s_setprio 1
	v_mfma_f32_16x16x32_bf16 v[24:27], v[8:11], v[220:223], v[140:143]
	v_mfma_f32_16x16x32_bf16 v[44:47], v[12:15], v[224:227], v[24:27]
	v_mfma_f32_16x16x32_bf16 v[24:27], v[16:19], v[220:223], v[144:147]
	v_mfma_f32_16x16x32_bf16 v[40:43], v[20:23], v[224:227], v[24:27]
	v_mfma_f32_16x16x32_bf16 v[24:27], v[8:11], v[228:231], v[148:151]
	v_mfma_f32_16x16x32_bf16 v[0:3], v[8:11], v[236:239], v[0:3]
	v_mfma_f32_16x16x32_bf16 v[28:31], v[12:15], v[232:235], v[24:27]
	v_mfma_f32_16x16x32_bf16 v[24:27], v[16:19], v[228:231], v[162:165]
	v_mfma_f32_16x16x32_bf16 v[12:15], v[12:15], v[240:243], v[0:3]
	v_mfma_f32_16x16x32_bf16 v[0:3], v[16:19], v[236:239], v[4:7]
	v_mfma_f32_16x16x32_bf16 v[24:27], v[20:23], v[232:235], v[24:27]
	v_mfma_f32_16x16x32_bf16 v[8:11], v[20:23], v[240:243], v[0:3]
	s_setprio 0
	s_setprio 1
	v_mfma_f32_16x16x32_bf16 v[0:3], v[204:207], v[32:35], v[166:169]
	v_mfma_f32_16x16x32_bf16 v[52:55], v[208:211], v[36:39], v[0:3]
	v_mfma_f32_16x16x32_bf16 v[0:3], v[212:215], v[32:35], v[170:173]
	v_mfma_f32_16x16x32_bf16 v[48:51], v[216:219], v[36:39], v[0:3]
	v_mfma_f32_16x16x32_bf16 v[0:3], v[204:207], v[220:223], v[174:177]
	v_mfma_f32_16x16x32_bf16 v[36:39], v[208:211], v[224:227], v[0:3]
	v_mfma_f32_16x16x32_bf16 v[0:3], v[212:215], v[220:223], v[178:181]
	v_mfma_f32_16x16x32_bf16 v[32:35], v[216:219], v[224:227], v[0:3]
	v_mfma_f32_16x16x32_bf16 v[0:3], v[204:207], v[228:231], v[182:185]
	v_mfma_f32_16x16x32_bf16 v[20:23], v[208:211], v[232:235], v[0:3]
	v_mfma_f32_16x16x32_bf16 v[0:3], v[212:215], v[228:231], v[186:189]
	v_mfma_f32_16x16x32_bf16 v[16:19], v[216:219], v[232:235], v[0:3]
	s_barrier
	v_mfma_f32_16x16x32_bf16 v[0:3], v[204:207], v[236:239], v[196:199]
	v_mfma_f32_16x16x32_bf16 v[4:7], v[208:211], v[240:243], v[0:3]
	v_mfma_f32_16x16x32_bf16 v[0:3], v[212:215], v[236:239], v[200:203]
	v_mfma_f32_16x16x32_bf16 v[0:3], v[216:219], v[240:243], v[0:3]
	s_setprio 0
	s_add_u32 s24, s48, 0x200
	s_addc_u32 s25, s49, 0
	s_add_u32 s38, s38, 0x40180
	s_addc_u32 s39, s39, 0

; #define PG8_STAGE(bufoff, gbase, voff) do { _Pragma("unroll") for (int _i = 0; _i < 2; ++_i) \
;         __builtin_amdgcn_global_load_lds((const GAS unsigned*)((const char*)(gbase) + (voff)[_i]), (LAS unsigned*)(lds + (bufoff) + ldsw + _i * 8192), 16, 0, 0); } while (0)
; #define PG8_LDA(dst, b, h) do { _Pragma("unroll") for (int m = 0; m < 4; ++m) _Pragma("unroll") for (int k = 0; k < 2; ++k) dst[m][k] = *(const LAS bf16x8*)(lds + PG8_SA(b, h) + aoff + m * 2048 + k * 1024); } while (0)
; #define PG8_LDB(dst, b, h) do { _Pragma("unroll") for (int n = 0; n < 2; ++n) _Pragma("unroll") for (int k = 0; k < 2; ++k) dst[n][k] = *(const LAS bf16x8*)(lds + PG8_SB(b, h) + boff + n * 2048 + k * 1024); } while (0)
; #define PG8_WAIT_V(n) asm volatile("s_waitcnt vmcnt(" #n ")" ::: "memory")
; #define PG8_WAIT_L(n) asm volatile("s_waitcnt lgkmcnt(" #n ")" ::: "memory")
; #define PG8_BAR __builtin_amdgcn_s_barrier()
; #define PG8_SCHED __builtin_amdgcn_sched_barrier(0)
; template <class Prog, bool ALIGN_EPI, bool NHALF = false, bool PITCHED = false, bool SLACK = false>
; __device__ __forceinline__ void gemm_phase(LAS unsigned char* lds, const int pitch, Prog& P, const int wave_, unsigned long long& t_k, unsigned long long& t_e) {
;     ...
;             PG8_LDB(B0, 0, 0); PG8_LDB(B1, 0, 1); PG8_SCHED; PG8_LDA(At, 0, 0); if (!(SLACK && SLACK_PRE && fst)) PG8_STAGE(PG8_SA(1, 1), a1 + hstep, voffA);
;             PG8_WAIT_F; PG8_WAIT_L(0); PG8_BAR; PG8_MMA(0, 0, At, B0); PG8_MMA(0, 1, At, B1); PG8_BAR; PG8_SCHED;
;             PG8_LDA(At, 0, 1); PG8_STAGE(PG8_SB(0, 0), b2, voffB2); PG8_STAGE(PG8_SB(0, 1), b2 + hstep2, voffB2); PG8_STAGE(PG8_SA(0, 0), a2, voffA2);
;             PG8_WAIT_F; PG8_WAIT_L(0); PG8_BAR; PG8_MMA(1, 0, At, B0); PG8_MMA(1, 1, At, B1); PG8_BAR; PG8_SCHED;
;             PG8_LDB(B0, 1, 0); PG8_LDB(B1, 1, 1); PG8_SCHED; PG8_LDA(At, 1, 0); PG8_STAGE(PG8_SA(0, 1), a2 + hstep2, voffA2);
;             if (SLACK_PRE) PG8_WAIT_F; else PG8_WAIT_V(8); PG8_WAIT_L(0); PG8_BAR; PG8_MMA(0, 0, At, B0); PG8_MMA(0, 1, At, B1); PG8_BAR; PG8_SCHED;
;             PG8_LDA(At, 1, 1); PG8_STAGE(PG8_SB(1, 0), b3, voffB2); PG8_STAGE(PG8_SB(1, 1), b3 + hstep2, voffB2); PG8_STAGE(PG8_SA(1, 0), a3, voffA2);
;             PG8_WAIT_V(8); PG8_WAIT_L(0); PG8_BAR; PG8_MMA(1, 0, At, B0); PG8_MMA(1, 1, At, B1); PG8_BAR; PG8_SCHED;
.Lwf2:
	s_waitcnt lgkmcnt(0)
	s_barrier
	s_waitcnt lgkmcnt(0)
	v_mfma_f32_16x16x32_bf16 v[124:127], v[132:135], v[174:177], v[124:127]
	v_mfma_f32_16x16x32_bf16 v[120:123], v[140:143], v[174:177], v[120:123]
	v_mfma_f32_16x16x32_bf16 v[108:111], v[132:135], v[182:185], v[108:111]
	v_mfma_f32_16x16x32_bf16 v[104:107], v[140:143], v[182:185], v[104:107]
	s_setprio 1
	v_mfma_f32_16x16x32_bf16 v[92:95], v[132:135], v[196:199], v[92:95]
	v_mfma_f32_16x16x32_bf16 v[88:91], v[140:143], v[196:199], v[88:91]
	v_mfma_f32_16x16x32_bf16 v[76:79], v[132:135], v[204:207], v[76:79]
	v_mfma_f32_16x16x32_bf16 v[72:75], v[140:143], v[204:207], v[72:75]
	v_mfma_f32_16x16x32_bf16 v[124:127], v[136:139], v[178:181], v[124:127]
	v_mfma_f32_16x16x32_bf16 v[120:123], v[144:147], v[178:181], v[120:123]
	v_mfma_f32_16x16x32_bf16 v[108:111], v[136:139], v[186:189], v[108:111]
	v_mfma_f32_16x16x32_bf16 v[104:107], v[144:147], v[186:189], v[104:107]
	v_mfma_f32_16x16x32_bf16 v[92:95], v[136:139], v[200:203], v[92:95]
	v_mfma_f32_16x16x32_bf16 v[88:91], v[144:147], v[200:203], v[88:91]
	v_mfma_f32_16x16x32_bf16 v[76:79], v[136:139], v[208:211], v[76:79]
	v_mfma_f32_16x16x32_bf16 v[72:75], v[144:147], v[208:211], v[72:75]
	s_setprio 0
	s_setprio 1
	v_mfma_f32_16x16x32_bf16 v[116:119], v[148:151], v[174:177], v[116:119]
	v_mfma_f32_16x16x32_bf16 v[112:115], v[166:169], v[174:177], v[112:115]
	v_mfma_f32_16x16x32_bf16 v[100:103], v[148:151], v[182:185], v[100:103]
	v_mfma_f32_16x16x32_bf16 v[96:99], v[166:169], v[182:185], v[96:99]
	v_mfma_f32_16x16x32_bf16 v[84:87], v[148:151], v[196:199], v[84:87]
	v_mfma_f32_16x16x32_bf16 v[80:83], v[166:169], v[196:199], v[80:83]
	v_mfma_f32_16x16x32_bf16 v[68:71], v[148:151], v[204:207], v[68:71]
	v_mfma_f32_16x16x32_bf16 v[64:67], v[166:169], v[204:207], v[64:67]
	v_mfma_f32_16x16x32_bf16 v[116:119], v[162:165], v[178:181], v[116:119]
	v_mfma_f32_16x16x32_bf16 v[112:115], v[170:173], v[178:181], v[112:115]
	v_mfma_f32_16x16x32_bf16 v[100:103], v[162:165], v[186:189], v[100:103]
	v_mfma_f32_16x16x32_bf16 v[96:99], v[170:173], v[186:189], v[96:99]
	s_barrier
	v_mfma_f32_16x16x32_bf16 v[84:87], v[162:165], v[200:203], v[84:87]
	v_mfma_f32_16x16x32_bf16 v[80:83], v[170:173], v[200:203], v[80:83]
	v_mfma_f32_16x16x32_bf16 v[68:71], v[162:165], v[208:211], v[68:71]
	v_mfma_f32_16x16x32_bf16 v[64:67], v[170:173], v[208:211], v[64:67]
	s_setprio 0
	s_mov_b32 m0, s8
	v_lshl_add_u64 v[190:191], s[48:49], 0, v[192:193]
	s_add_u32 s34, s48, 0x40000
	ds_read_b128 v[174:177], v252 offset:16384
	ds_read_b128 v[178:181], v252 offset:17408
	ds_read_b128 v[182:185], v252 offset:18432
	ds_read_b128 v[186:189], v252 offset:19456
	ds_read_b128 v[196:199], v252 offset:20480
	ds_read_b128 v[200:203], v252 offset:21504
	ds_read_b128 v[204:207], v252 offset:22528
	ds_read_b128 v[208:211], v252 offset:23552
	global_load_lds_dwordx4 v[190:191], off
	v_lshl_add_u64 v[194:195], s[48:49], 0, v[156:157]
	s_mov_b32 m0, s9
	s_addc_u32 s35, s49, 0
	global_load_lds_dwordx4 v[194:195], off
	v_lshl_add_u64 v[212:213], s[34:35], 0, v[192:193]
	s_mov_b32 m0, s10
	v_lshl_add_u64 v[214:215], s[50:51], 0, v[154:155]
	global_load_lds_dwordx4 v[212:213], off
	v_lshl_add_u64 v[212:213], s[34:35], 0, v[156:157]
	s_mov_b32 m0, s11
	s_nop 0
	global_load_lds_dwordx4 v[212:213], off
	v_lshl_add_u64 v[212:213], s[50:51], 0, v[152:153]
	s_mov_b32 m0, s60
	s_nop 0
	global_load_lds_dwordx4 v[212:213], off
	s_mov_b32 m0, s61
	s_nop 0
	global_load_lds_dwordx4 v[214:215], off
	s_waitcnt vmcnt(24)
	s_cmp_gt_u32 s79, 1
	s_cbranch_scc1 .Lwf3
	s_waitcnt vmcnt(16)
	s_cmp_gt_u32 s79, 0
	s_cbranch_scc1 .Lwf3
	s_waitcnt vmcnt(8)
.Lwf3:
	s_waitcnt lgkmcnt(0)
	s_barrier
	s_waitcnt lgkmcnt(0)
	v_mfma_f32_16x16x32_bf16 v[60:63], v[132:135], v[174:177], v[60:63]
	v_mfma_f32_16x16x32_bf16 v[56:59], v[140:143], v[174:177], v[56:59]
	v_mfma_f32_16x16x32_bf16 v[44:47], v[132:135], v[182:185], v[44:47]
	v_mfma_f32_16x16x32_bf16 v[40:43], v[140:143], v[182:185], v[40:43]
	s_setprio 1
	v_mfma_f32_16x16x32_bf16 v[28:31], v[132:135], v[196:199], v[28:31]
	v_mfma_f32_16x16x32_bf16 v[24:27], v[140:143], v[196:199], v[24:27]
	v_mfma_f32_16x16x32_bf16 v[12:15], v[132:135], v[204:207], v[12:15]
	v_mfma_f32_16x16x32_bf16 v[8:11], v[140:143], v[204:207], v[8:11]
	v_mfma_f32_16x16x32_bf16 v[60:63], v[136:139], v[178:181], v[60:63]
	v_mfma_f32_16x16x32_bf16 v[56:59], v[144:147], v[178:181], v[56:59]
	v_mfma_f32_16x16x32_bf16 v[44:47], v[136:139], v[186:189], v[44:47]
	v_mfma_f32_16x16x32_bf16 v[40:43], v[144:147], v[186:189], v[40:43]
	v_mfma_f32_16x16x32_bf16 v[28:31], v[136:139], v[200:203], v[28:31]
	v_mfma_f32_16x16x32_bf16 v[24:27], v[144:147], v[200:203], v[24:27]
	v_mfma_f32_16x16x32_bf16 v[12:15], v[136:139], v[208:211], v[12:15]
	v_mfma_f32_16x16x32_bf16 v[8:11], v[144:147], v[208:211], v[8:11]
	s_setprio 0
	s_setprio 1
	v_mfma_f32_16x16x32_bf16 v[52:55], v[148:151], v[174:177], v[52:55]
	v_mfma_f32_16x16x32_bf16 v[48:51], v[166:169], v[174:177], v[48:51]
	v_mfma_f32_16x16x32_bf16 v[36:39], v[148:151], v[182:185], v[36:39]
	v_mfma_f32_16x16x32_bf16 v[32:35], v[166:169], v[182:185], v[32:35]
	v_mfma_f32_16x16x32_bf16 v[20:23], v[148:151], v[196:199], v[20:23]
	v_mfma_f32_16x16x32_bf16 v[16:19], v[166:169], v[196:199], v[16:19]
	v_mfma_f32_16x16x32_bf16 v[4:7], v[148:151], v[204:207], v[4:7]
	v_mfma_f32_16x16x32_bf16 v[0:3], v[166:169], v[204:207], v[0:3]
	v_mfma_f32_16x16x32_bf16 v[52:55], v[162:165], v[178:181], v[52:55]
	v_mfma_f32_16x16x32_bf16 v[48:51], v[170:173], v[178:181], v[48:51]
	v_mfma_f32_16x16x32_bf16 v[36:39], v[162:165], v[186:189], v[36:39]
	v_mfma_f32_16x16x32_bf16 v[32:35], v[170:173], v[186:189], v[32:35]
	s_barrier
; #define PG8_STAGE(bufoff, gbase, voff) do { _Pragma("unroll") for (int _i = 0; _i < 2; ++_i) \
;         __builtin_amdgcn_global_load_lds((const GAS unsigned*)((const char*)(gbase) + (voff)[_i]), (LAS unsigned*)(lds + (bufoff) + ldsw + _i * 8192), 16, 0, 0); } while (0)
; #define PG8_LDA(dst, b, h) do { _Pragma("unroll") for (int m = 0; m < 4; ++m) _Pragma("unroll") for (int k = 0; k < 2; ++k) dst[m][k] = *(const LAS bf16x8*)(lds + PG8_SA(b, h) + aoff + m * 2048 + k * 1024); } while (0)
; #define PG8_LDB(dst, b, h) do { _Pragma("unroll") for (int n = 0; n < 2; ++n) _Pragma("unroll") for (int k = 0; k < 2; ++k) dst[n][k] = *(const LAS bf16x8*)(lds + PG8_SB(b, h) + boff + n * 2048 + k * 1024); } while (0)
; #define PG8_WAIT_V(n) asm volatile("s_waitcnt vmcnt(" #n ")" ::: "memory")
; #define PG8_WAIT_L(n) asm volatile("s_waitcnt lgkmcnt(" #n ")" ::: "memory")
; #define PG8_BAR __builtin_amdgcn_s_barrier()
; #define PG8_SCHED __builtin_amdgcn_sched_barrier(0)
; template <class Prog, bool ALIGN_EPI, bool NHALF = false, bool PITCHED = false, bool SLACK = false>
; __device__ __forceinline__ void gemm_phase(LAS unsigned char* lds, const int pitch, Prog& P, const int wave_, unsigned long long& t_k, unsigned long long& t_e) {
;     ...
;             PG8_LDB(B0, 0, 0); PG8_LDB(B1, 0, 1); PG8_SCHED; PG8_LDA(At, 0, 0); if (!(SLACK && SLACK_PRE && fst)) PG8_STAGE(PG8_SA(1, 1), a1 + hstep, voffA);
;             PG8_WAIT_F; PG8_WAIT_L(0); PG8_BAR; PG8_MMA(0, 0, At, B0); PG8_MMA(0, 1, At, B1); PG8_BAR; PG8_SCHED;
;             PG8_LDA(At, 0, 1); PG8_STAGE(PG8_SB(0, 0), b2, voffB2); PG8_STAGE(PG8_SB(0, 1), b2 + hstep2, voffB2); PG8_STAGE(PG8_SA(0, 0), a2, voffA2);
;             PG8_WAIT_F; PG8_WAIT_L(0); PG8_BAR; PG8_MMA(1, 0, At, B0); PG8_MMA(1, 1, At, B1); PG8_BAR; PG8_SCHED;
;             PG8_LDB(B0, 1, 0); PG8_LDB(B1, 1, 1); PG8_SCHED; PG8_LDA(At, 1, 0); PG8_STAGE(PG8_SA(0, 1), a2 + hstep2, voffA2);
;             if (SLACK_PRE) PG8_WAIT_F; else PG8_WAIT_V(8); PG8_WAIT_L(0); PG8_BAR; PG8_MMA(0, 0, At, B0); PG8_MMA(0, 1, At, B1); PG8_BAR; PG8_SCHED;
;             PG8_LDA(At, 1, 1); PG8_STAGE(PG8_SB(1, 0), b3, voffB2); PG8_STAGE(PG8_SB(1, 1), b3 + hstep2, voffB2); PG8_STAGE(PG8_SA(1, 0), a3, voffA2);
;             PG8_WAIT_V(8); PG8_WAIT_L(0); PG8_BAR; PG8_MMA(1, 0, At, B0); PG8_MMA(1, 1, At, B1); PG8_BAR; PG8_SCHED;
	v_mfma_f32_16x16x32_bf16 v[20:23], v[162:165], v[200:203], v[20:23]
	v_mfma_f32_16x16x32_bf16 v[16:19], v[170:173], v[200:203], v[16:19]
	v_mfma_f32_16x16x32_bf16 v[4:7], v[162:165], v[208:211], v[4:7]
	v_mfma_f32_16x16x32_bf16 v[0:3], v[170:173], v[208:211], v[0:3]
	s_setprio 0
	ds_read_b128 v[132:135], v130
	ds_read_b128 v[136:139], v130 offset:1024
	ds_read_b128 v[140:143], v130 offset:2048
	ds_read_b128 v[144:147], v130 offset:3072
	ds_read_b128 v[148:151], v131
	ds_read_b128 v[162:165], v131 offset:1024
	ds_read_b128 v[166:169], v131 offset:2048
	ds_read_b128 v[170:173], v131 offset:3072
	s_add_u32 s34, s50, 0x40000
	s_addc_u32 s35, s51, 0
	s_mov_b32 m0, s62
	v_lshl_add_u64 v[216:217], s[34:35], 0, v[152:153]
	ds_read_b128 v[174:177], v252 offset:32768
	ds_read_b128 v[178:181], v252 offset:33792
	ds_read_b128 v[182:185], v252 offset:34816
	ds_read_b128 v[186:189], v252 offset:35840
	ds_read_b128 v[196:199], v252 offset:36864
	ds_read_b128 v[200:203], v252 offset:37888
	ds_read_b128 v[204:207], v252 offset:38912
	ds_read_b128 v[208:211], v252 offset:39936
	global_load_lds_dwordx4 v[216:217], off
	v_lshl_add_u64 v[216:217], s[34:35], 0, v[154:155]
	s_mov_b32 m0, s63
	s_nop 0
	global_load_lds_dwordx4 v[216:217], off
	s_waitcnt vmcnt(8)
	s_waitcnt lgkmcnt(0)
	s_barrier
	s_waitcnt lgkmcnt(0)
	v_mfma_f32_16x16x32_bf16 v[124:127], v[132:135], v[174:177], v[124:127]
	v_mfma_f32_16x16x32_bf16 v[120:123], v[140:143], v[174:177], v[120:123]
	v_mfma_f32_16x16x32_bf16 v[108:111], v[132:135], v[182:185], v[108:111]
	v_mfma_f32_16x16x32_bf16 v[104:107], v[140:143], v[182:185], v[104:107]
	s_setprio 1
	v_mfma_f32_16x16x32_bf16 v[92:95], v[132:135], v[196:199], v[92:95]
	v_mfma_f32_16x16x32_bf16 v[88:91], v[140:143], v[196:199], v[88:91]
	v_mfma_f32_16x16x32_bf16 v[76:79], v[132:135], v[204:207], v[76:79]
	v_mfma_f32_16x16x32_bf16 v[72:75], v[140:143], v[204:207], v[72:75]
	v_mfma_f32_16x16x32_bf16 v[124:127], v[136:139], v[178:181], v[124:127]
	v_mfma_f32_16x16x32_bf16 v[120:123], v[144:147], v[178:181], v[120:123]
	v_mfma_f32_16x16x32_bf16 v[108:111], v[136:139], v[186:189], v[108:111]
	v_mfma_f32_16x16x32_bf16 v[104:107], v[144:147], v[186:189], v[104:107]
	v_mfma_f32_16x16x32_bf16 v[92:95], v[136:139], v[200:203], v[92:95]
	v_mfma_f32_16x16x32_bf16 v[88:91], v[144:147], v[200:203], v[88:91]
	v_mfma_f32_16x16x32_bf16 v[76:79], v[136:139], v[208:211], v[76:79]
	v_mfma_f32_16x16x32_bf16 v[72:75], v[144:147], v[208:211], v[72:75]
	s_setprio 0
	s_setprio 1
	v_mfma_f32_16x16x32_bf16 v[116:119], v[148:151], v[174:177], v[116:119]
	v_mfma_f32_16x16x32_bf16 v[112:115], v[166:169], v[174:177], v[112:115]
	v_mfma_f32_16x16x32_bf16 v[100:103], v[148:151], v[182:185], v[100:103]
	v_mfma_f32_16x16x32_bf16 v[96:99], v[166:169], v[182:185], v[96:99]
	v_mfma_f32_16x16x32_bf16 v[84:87], v[148:151], v[196:199], v[84:87]
	v_mfma_f32_16x16x32_bf16 v[80:83], v[166:169], v[196:199], v[80:83]
	v_mfma_f32_16x16x32_bf16 v[68:71], v[148:151], v[204:207], v[68:71]
	v_mfma_f32_16x16x32_bf16 v[64:67], v[166:169], v[204:207], v[64:67]
	v_mfma_f32_16x16x32_bf16 v[116:119], v[162:165], v[178:181], v[116:119]
	v_mfma_f32_16x16x32_bf16 v[112:115], v[170:173], v[178:181], v[112:115]
	v_mfma_f32_16x16x32_bf16 v[100:103], v[162:165], v[186:189], v[100:103]
	v_mfma_f32_16x16x32_bf16 v[96:99], v[170:173], v[186:189], v[96:99]
	s_barrier
; #define PG8_STAGE(bufoff, gbase, voff) do { _Pragma("unroll") for (int _i = 0; _i < 2; ++_i) \
;         __builtin_amdgcn_global_load_lds((const GAS unsigned*)((const char*)(gbase) + (voff)[_i]), (LAS unsigned*)(lds + (bufoff) + ldsw + _i * 8192), 16, 0, 0); } while (0)
; #define PG8_LDA(dst, b, h) do { _Pragma("unroll") for (int m = 0; m < 4; ++m) _Pragma("unroll") for (int k = 0; k < 2; ++k) dst[m][k] = *(const LAS bf16x8*)(lds + PG8_SA(b, h) + aoff + m * 2048 + k * 1024); } while (0)
; #define PG8_LDB(dst, b, h) do { _Pragma("unroll") for (int n = 0; n < 2; ++n) _Pragma("unroll") for (int k = 0; k < 2; ++k) dst[n][k] = *(const LAS bf16x8*)(lds + PG8_SB(b, h) + boff + n * 2048 + k * 1024); } while (0)
; #define PG8_WAIT_V(n) asm volatile("s_waitcnt vmcnt(" #n ")" ::: "memory")
; #define PG8_WAIT_L(n) asm volatile("s_waitcnt lgkmcnt(" #n ")" ::: "memory")
; #define PG8_BAR __builtin_amdgcn_s_barrier()
; #define PG8_SCHED __builtin_amdgcn_sched_barrier(0)
; template <class Prog, bool ALIGN_EPI, bool NHALF = false, bool PITCHED = false, bool SLACK = false>
; __device__ __forceinline__ void gemm_phase(LAS unsigned char* lds, const int pitch, Prog& P, const int wave_, unsigned long long& t_k, unsigned long long& t_e) {
;     ...
;         for (int t = 0; t < nt; t += 2) {
;     ...
;             PG8_LDB(B0, 0, 0); PG8_LDB(B1, 0, 1); PG8_SCHED; PG8_LDA(At, 0, 0); if (!(SLACK && SLACK_PRE && fst)) PG8_STAGE(PG8_SA(1, 1), a1 + hstep, voffA);
;             PG8_WAIT_F; PG8_WAIT_L(0); PG8_BAR; PG8_MMA(0, 0, At, B0); PG8_MMA(0, 1, At, B1); PG8_BAR; PG8_SCHED;
;             PG8_LDA(At, 0, 1); PG8_STAGE(PG8_SB(0, 0), b2, voffB2); PG8_STAGE(PG8_SB(0, 1), b2 + hstep2, voffB2); PG8_STAGE(PG8_SA(0, 0), a2, voffA2);
;             PG8_WAIT_F; PG8_WAIT_L(0); PG8_BAR; PG8_MMA(1, 0, At, B0); PG8_MMA(1, 1, At, B1); PG8_BAR; PG8_SCHED;
;             PG8_LDB(B0, 1, 0); PG8_LDB(B1, 1, 1); PG8_SCHED; PG8_LDA(At, 1, 0); PG8_STAGE(PG8_SA(0, 1), a2 + hstep2, voffA2);
;             if (SLACK_PRE) PG8_WAIT_F; else PG8_WAIT_V(8); PG8_WAIT_L(0); PG8_BAR; PG8_MMA(0, 0, At, B0); PG8_MMA(0, 1, At, B1); PG8_BAR; PG8_SCHED;
;             PG8_LDA(At, 1, 1); PG8_STAGE(PG8_SB(1, 0), b3, voffB2); PG8_STAGE(PG8_SB(1, 1), b3 + hstep2, voffB2); PG8_STAGE(PG8_SA(1, 0), a3, voffA2);
;             PG8_WAIT_V(8); PG8_WAIT_L(0); PG8_BAR; PG8_MMA(1, 0, At, B0); PG8_MMA(1, 1, At, B1); PG8_BAR; PG8_SCHED;
	v_mfma_f32_16x16x32_bf16 v[84:87], v[162:165], v[200:203], v[84:87]
	v_mfma_f32_16x16x32_bf16 v[80:83], v[170:173], v[200:203], v[80:83]
	v_mfma_f32_16x16x32_bf16 v[68:71], v[162:165], v[208:211], v[68:71]
	v_mfma_f32_16x16x32_bf16 v[64:67], v[170:173], v[208:211], v[64:67]
	s_setprio 0
	s_mov_b32 m0, s16
	v_lshl_add_u64 v[190:191], v[190:191], 0, s[12:13]
	s_add_u32 s34, s48, 0x40080
	ds_read_b128 v[174:177], v252 offset:49152
	ds_read_b128 v[178:181], v252 offset:50176
	ds_read_b128 v[182:185], v252 offset:51200
	ds_read_b128 v[186:189], v252 offset:52224
	ds_read_b128 v[196:199], v252 offset:53248
	ds_read_b128 v[200:203], v252 offset:54272
	ds_read_b128 v[204:207], v252 offset:55296
	ds_read_b128 v[208:211], v252 offset:56320
	global_load_lds_dwordx4 v[190:191], off
	v_lshl_add_u64 v[190:191], v[194:195], 0, s[12:13]
	s_mov_b32 m0, s17
	s_addc_u32 s35, s49, 0
	global_load_lds_dwordx4 v[190:191], off
	v_lshl_add_u64 v[190:191], s[34:35], 0, v[192:193]
	s_mov_b32 m0, s18
	s_nop 0
	global_load_lds_dwordx4 v[190:191], off
	v_lshl_add_u64 v[190:191], s[34:35], 0, v[156:157]
	s_mov_b32 m0, s19
	s_nop 0
	global_load_lds_dwordx4 v[190:191], off
	v_lshl_add_u64 v[190:191], v[212:213], 0, s[12:13]
	s_mov_b32 m0, s81
	s_nop 0
	global_load_lds_dwordx4 v[190:191], off
	v_lshl_add_u64 v[190:191], v[214:215], 0, s[12:13]
	s_mov_b32 m0, s82
	s_nop 0
	global_load_lds_dwordx4 v[190:191], off
	s_waitcnt vmcnt(8)
	s_waitcnt lgkmcnt(0)
	s_barrier
	s_waitcnt lgkmcnt(0)
	v_mfma_f32_16x16x32_bf16 v[60:63], v[132:135], v[174:177], v[60:63]
	v_mfma_f32_16x16x32_bf16 v[56:59], v[140:143], v[174:177], v[56:59]
	v_mfma_f32_16x16x32_bf16 v[44:47], v[132:135], v[182:185], v[44:47]
	v_mfma_f32_16x16x32_bf16 v[40:43], v[140:143], v[182:185], v[40:43]
	s_setprio 1
	v_mfma_f32_16x16x32_bf16 v[28:31], v[132:135], v[196:199], v[28:31]
	v_mfma_f32_16x16x32_bf16 v[24:27], v[140:143], v[196:199], v[24:27]
	v_mfma_f32_16x16x32_bf16 v[12:15], v[132:135], v[204:207], v[12:15]
	v_mfma_f32_16x16x32_bf16 v[8:11], v[140:143], v[204:207], v[8:11]
	v_mfma_f32_16x16x32_bf16 v[60:63], v[136:139], v[178:181], v[60:63]
	v_mfma_f32_16x16x32_bf16 v[56:59], v[144:147], v[178:181], v[56:59]
	v_mfma_f32_16x16x32_bf16 v[44:47], v[136:139], v[186:189], v[44:47]
	v_mfma_f32_16x16x32_bf16 v[40:43], v[144:147], v[186:189], v[40:43]
	v_mfma_f32_16x16x32_bf16 v[28:31], v[136:139], v[200:203], v[28:31]
	v_mfma_f32_16x16x32_bf16 v[24:27], v[144:147], v[200:203], v[24:27]
	v_mfma_f32_16x16x32_bf16 v[12:15], v[136:139], v[208:211], v[12:15]
	v_mfma_f32_16x16x32_bf16 v[8:11], v[144:147], v[208:211], v[8:11]
	s_setprio 0
	s_setprio 1
	v_mfma_f32_16x16x32_bf16 v[52:55], v[148:151], v[174:177], v[52:55]
	v_mfma_f32_16x16x32_bf16 v[48:51], v[166:169], v[174:177], v[48:51]
	v_mfma_f32_16x16x32_bf16 v[36:39], v[148:151], v[182:185], v[36:39]
	v_mfma_f32_16x16x32_bf16 v[32:35], v[166:169], v[182:185], v[32:35]
	v_mfma_f32_16x16x32_bf16 v[20:23], v[148:151], v[196:199], v[20:23]
	v_mfma_f32_16x16x32_bf16 v[16:19], v[166:169], v[196:199], v[16:19]
	v_mfma_f32_16x16x32_bf16 v[4:7], v[148:151], v[204:207], v[4:7]
	v_mfma_f32_16x16x32_bf16 v[0:3], v[166:169], v[204:207], v[0:3]
	v_mfma_f32_16x16x32_bf16 v[52:55], v[162:165], v[178:181], v[52:55]
	v_mfma_f32_16x16x32_bf16 v[48:51], v[170:173], v[178:181], v[48:51]
	v_mfma_f32_16x16x32_bf16 v[36:39], v[162:165], v[186:189], v[36:39]
	v_mfma_f32_16x16x32_bf16 v[32:35], v[170:173], v[186:189], v[32:35]
	s_barrier
	v_mfma_f32_16x16x32_bf16 v[20:23], v[162:165], v[200:203], v[20:23]
	v_mfma_f32_16x16x32_bf16 v[16:19], v[170:173], v[200:203], v[16:19]
	v_mfma_f32_16x16x32_bf16 v[4:7], v[162:165], v[208:211], v[4:7]
	v_mfma_f32_16x16x32_bf16 v[0:3], v[170:173], v[208:211], v[0:3]
	s_setprio 0
	s_add_i32 s0, s0, 2
	s_add_u32 s24, s24, 0x100
	s_addc_u32 s25, s25, 0
	s_add_u32 s38, s38, 0x100
	s_addc_u32 s39, s39, 0
	s_cmp_gt_u32 s0, 13
	s_cbranch_scc0 .LBB0_200
	s_and_b64 vcc, exec, s[74:75]
	s_cbranch_vccz .LBB0_203
	s_barrier
